# one static s_setprio 1 for waves 0-3 (other half) before the P5 and P6' K-loops, per-segment flips deleted; rest as v058
# speedup vs baseline: 1.0042x; 1.0003x over previous
.LBB0_506:
	s_add_u32 s42, s42, 0x80080
	s_addc_u32 s43, s43, 0
	s_add_u32 s17, s44, 0x100
	v_mov_b32_e32 v0, 0
	s_addc_u32 s21, s45, 0
	s_mov_b32 s52, -2
	v_mov_b32_e32 v1, v0
	v_mov_b32_e32 v2, v0
	v_mov_b32_e32 v3, v0
	v_mov_b32_e32 v4, v0
	v_mov_b32_e32 v5, v0
	v_mov_b32_e32 v6, v0
	v_mov_b32_e32 v7, v0
	v_mov_b32_e32 v16, v0
	v_mov_b32_e32 v17, v0
	v_mov_b32_e32 v18, v0
	v_mov_b32_e32 v19, v0
	v_mov_b32_e32 v20, v0
	v_mov_b32_e32 v21, v0
	v_mov_b32_e32 v22, v0
	v_mov_b32_e32 v23, v0
	v_mov_b32_e32 v32, v0
	v_mov_b32_e32 v33, v0
	v_mov_b32_e32 v34, v0
	v_mov_b32_e32 v35, v0
	v_mov_b32_e32 v36, v0
	v_mov_b32_e32 v37, v0
	v_mov_b32_e32 v38, v0
	v_mov_b32_e32 v39, v0
	v_mov_b32_e32 v48, v0
	v_mov_b32_e32 v49, v0
	v_mov_b32_e32 v50, v0
	v_mov_b32_e32 v51, v0
	v_mov_b32_e32 v52, v0
	v_mov_b32_e32 v53, v0
	v_mov_b32_e32 v54, v0
	v_mov_b32_e32 v55, v0
	v_mov_b32_e32 v8, v0
	v_mov_b32_e32 v9, v0
	v_mov_b32_e32 v10, v0
	v_mov_b32_e32 v11, v0
	v_mov_b32_e32 v12, v0
	v_mov_b32_e32 v13, v0
	v_mov_b32_e32 v14, v0
	v_mov_b32_e32 v15, v0
	v_mov_b32_e32 v24, v0
	v_mov_b32_e32 v25, v0
	v_mov_b32_e32 v26, v0
	v_mov_b32_e32 v27, v0
	v_mov_b32_e32 v28, v0
	v_mov_b32_e32 v29, v0
	v_mov_b32_e32 v30, v0
	v_mov_b32_e32 v31, v0
	v_mov_b32_e32 v40, v0
	v_mov_b32_e32 v41, v0
	v_mov_b32_e32 v42, v0
	v_mov_b32_e32 v43, v0
	v_mov_b32_e32 v44, v0
	v_mov_b32_e32 v45, v0
	v_mov_b32_e32 v46, v0
	v_mov_b32_e32 v47, v0
	v_mov_b32_e32 v56, v0
	v_mov_b32_e32 v57, v0
	v_mov_b32_e32 v58, v0
	v_mov_b32_e32 v59, v0
	v_mov_b32_e32 v60, v0
	v_mov_b32_e32 v61, v0
	v_mov_b32_e32 v62, v0
	v_mov_b32_e32 v63, v0
	v_mov_b32_e32 v64, v0
	v_mov_b32_e32 v65, v0
	v_mov_b32_e32 v66, v0
	v_mov_b32_e32 v67, v0
	v_mov_b32_e32 v68, v0
	v_mov_b32_e32 v69, v0
	v_mov_b32_e32 v70, v0
	v_mov_b32_e32 v71, v0
	v_mov_b32_e32 v80, v0
	v_mov_b32_e32 v81, v0
	v_mov_b32_e32 v82, v0
	v_mov_b32_e32 v83, v0
	v_mov_b32_e32 v84, v0
	v_mov_b32_e32 v85, v0
	v_mov_b32_e32 v86, v0
	v_mov_b32_e32 v87, v0
	v_mov_b32_e32 v96, v0
	v_mov_b32_e32 v97, v0
	v_mov_b32_e32 v98, v0
	v_mov_b32_e32 v99, v0
	v_mov_b32_e32 v100, v0
	v_mov_b32_e32 v101, v0
	v_mov_b32_e32 v102, v0
	v_mov_b32_e32 v103, v0
	v_mov_b32_e32 v112, v0
	v_mov_b32_e32 v113, v0
	v_mov_b32_e32 v114, v0
	v_mov_b32_e32 v115, v0
	v_mov_b32_e32 v116, v0
	v_mov_b32_e32 v117, v0
	v_mov_b32_e32 v118, v0
	v_mov_b32_e32 v119, v0
	v_mov_b32_e32 v72, v0
	v_mov_b32_e32 v73, v0
	v_mov_b32_e32 v74, v0
	v_mov_b32_e32 v75, v0
	v_mov_b32_e32 v76, v0
	v_mov_b32_e32 v77, v0
	v_mov_b32_e32 v78, v0
	v_mov_b32_e32 v79, v0
	v_mov_b32_e32 v88, v0
	v_mov_b32_e32 v89, v0
	v_mov_b32_e32 v90, v0
	v_mov_b32_e32 v91, v0
	v_mov_b32_e32 v92, v0
	v_mov_b32_e32 v93, v0
	v_mov_b32_e32 v94, v0
	v_mov_b32_e32 v95, v0
	v_mov_b32_e32 v104, v0
	v_mov_b32_e32 v105, v0
	v_mov_b32_e32 v106, v0
	v_mov_b32_e32 v107, v0
	v_mov_b32_e32 v108, v0
	v_mov_b32_e32 v109, v0
	v_mov_b32_e32 v110, v0
	v_mov_b32_e32 v111, v0
	v_mov_b32_e32 v120, v0
	v_mov_b32_e32 v121, v0
	v_mov_b32_e32 v122, v0
	v_mov_b32_e32 v123, v0
	v_mov_b32_e32 v124, v0
	v_mov_b32_e32 v125, v0
	v_mov_b32_e32 v126, v0
	v_mov_b32_e32 v127, v0
	v_readlane_b32 s54, v254, 6
	s_nop 3
	s_cmp_ge_u32 s54, 0x100
	s_cbranch_scc1 .Lsprio_p5
	s_setprio 1

.LBB0_673:
	s_and_b64 s[30:31], s[22:23], exec
	s_cselect_b32 s3, s11, s25
	s_cselect_b32 s29, s10, s24
	s_add_u32 s24, s24, 0xc000
	v_mov_b32_e32 v0, 0
	s_addc_u32 s25, s25, 0
	s_mov_b32 s45, -2
	s_mov_b64 s[30:31], s[20:21]
	v_mov_b32_e32 v1, v0
	v_mov_b32_e32 v2, v0
	v_mov_b32_e32 v3, v0
	v_mov_b32_e32 v4, v0
	v_mov_b32_e32 v5, v0
	v_mov_b32_e32 v6, v0
	v_mov_b32_e32 v7, v0
	v_mov_b32_e32 v16, v0
	v_mov_b32_e32 v17, v0
	v_mov_b32_e32 v18, v0
	v_mov_b32_e32 v19, v0
	v_mov_b32_e32 v20, v0
	v_mov_b32_e32 v21, v0
	v_mov_b32_e32 v22, v0
	v_mov_b32_e32 v23, v0
	v_mov_b32_e32 v32, v0
	v_mov_b32_e32 v33, v0
	v_mov_b32_e32 v34, v0
	v_mov_b32_e32 v35, v0
	v_mov_b32_e32 v36, v0
	v_mov_b32_e32 v37, v0
	v_mov_b32_e32 v38, v0
	v_mov_b32_e32 v39, v0
	v_mov_b32_e32 v48, v0
	v_mov_b32_e32 v49, v0
	v_mov_b32_e32 v50, v0
	v_mov_b32_e32 v51, v0
	v_mov_b32_e32 v52, v0
	v_mov_b32_e32 v53, v0
	v_mov_b32_e32 v54, v0
	v_mov_b32_e32 v55, v0
	v_mov_b32_e32 v8, v0
	v_mov_b32_e32 v9, v0
	v_mov_b32_e32 v10, v0
	v_mov_b32_e32 v11, v0
	v_mov_b32_e32 v12, v0
	v_mov_b32_e32 v13, v0
	v_mov_b32_e32 v14, v0
	v_mov_b32_e32 v15, v0
	v_mov_b32_e32 v24, v0
	v_mov_b32_e32 v25, v0
	v_mov_b32_e32 v26, v0
	v_mov_b32_e32 v27, v0
	v_mov_b32_e32 v28, v0
	v_mov_b32_e32 v29, v0
	v_mov_b32_e32 v30, v0
	v_mov_b32_e32 v31, v0
	v_mov_b32_e32 v40, v0
	v_mov_b32_e32 v41, v0
	v_mov_b32_e32 v42, v0
	v_mov_b32_e32 v43, v0
	v_mov_b32_e32 v44, v0
	v_mov_b32_e32 v45, v0
	v_mov_b32_e32 v46, v0
	v_mov_b32_e32 v47, v0
	v_mov_b32_e32 v56, v0
	v_mov_b32_e32 v57, v0
	v_mov_b32_e32 v58, v0
	v_mov_b32_e32 v59, v0
	v_mov_b32_e32 v60, v0
	v_mov_b32_e32 v61, v0
	v_mov_b32_e32 v62, v0
	v_mov_b32_e32 v63, v0
	v_mov_b32_e32 v64, v0
	v_mov_b32_e32 v65, v0
	v_mov_b32_e32 v66, v0
	v_mov_b32_e32 v67, v0
	v_mov_b32_e32 v68, v0
	v_mov_b32_e32 v69, v0
	v_mov_b32_e32 v70, v0
	v_mov_b32_e32 v71, v0
	v_mov_b32_e32 v80, v0
	v_mov_b32_e32 v81, v0
	v_mov_b32_e32 v82, v0
	v_mov_b32_e32 v83, v0
	v_mov_b32_e32 v84, v0
	v_mov_b32_e32 v85, v0
	v_mov_b32_e32 v86, v0
	v_mov_b32_e32 v87, v0
	v_mov_b32_e32 v96, v0
	v_mov_b32_e32 v97, v0
	v_mov_b32_e32 v98, v0
	v_mov_b32_e32 v99, v0
	v_mov_b32_e32 v100, v0
	v_mov_b32_e32 v101, v0
	v_mov_b32_e32 v102, v0
	v_mov_b32_e32 v103, v0
	v_mov_b32_e32 v112, v0
	v_mov_b32_e32 v113, v0
	v_mov_b32_e32 v114, v0
	v_mov_b32_e32 v115, v0
	v_mov_b32_e32 v116, v0
	v_mov_b32_e32 v117, v0
	v_mov_b32_e32 v118, v0
	v_mov_b32_e32 v119, v0
	v_mov_b32_e32 v72, v0
	v_mov_b32_e32 v73, v0
	v_mov_b32_e32 v74, v0
	v_mov_b32_e32 v75, v0
	v_mov_b32_e32 v76, v0
	v_mov_b32_e32 v77, v0
	v_mov_b32_e32 v78, v0
	v_mov_b32_e32 v79, v0
	v_mov_b32_e32 v88, v0
	v_mov_b32_e32 v89, v0
	v_mov_b32_e32 v90, v0
	v_mov_b32_e32 v91, v0
	v_mov_b32_e32 v92, v0
	v_mov_b32_e32 v93, v0
	v_mov_b32_e32 v94, v0
	v_mov_b32_e32 v95, v0
	v_mov_b32_e32 v104, v0
	v_mov_b32_e32 v105, v0
	v_mov_b32_e32 v106, v0
	v_mov_b32_e32 v107, v0
	v_mov_b32_e32 v108, v0
	v_mov_b32_e32 v109, v0
	v_mov_b32_e32 v110, v0
	v_mov_b32_e32 v111, v0
	v_mov_b32_e32 v120, v0
	v_mov_b32_e32 v121, v0
	v_mov_b32_e32 v122, v0
	v_mov_b32_e32 v123, v0
	v_mov_b32_e32 v124, v0
	v_mov_b32_e32 v125, v0
	v_mov_b32_e32 v126, v0
	v_mov_b32_e32 v127, v0
	v_readlane_b32 s36, v254, 6
	s_nop 3
	s_cmp_ge_u32 s36, 0x100
	s_cbranch_scc1 .Lsprio_p6
	s_setprio 1
